# baseline (speedup 1.0000x reference)
; __global__ void __launch_bounds__(512) fwd_megakernel(Args args) {
;     ...
;             float ga = 0.f, gk = 0.f, gb = 0.f, gl = 0.f, sk = 0.f, rb = 0.f;
;             for (int j = 0; j < 64; ++j) { ga = fmaxf(ga, fabsf(args.in[6][j])); gk = fmaxf(gk, fabsf(args.in[7][j])); gb = fmaxf(gb, fabsf(args.in[9][j])); gl = fmaxf(gl, fabsf(args.in[10][j])); }
;             for (int j = 0; j < 8; ++j) sk = fmaxf(sk, fabsf(args.in[8][j]));
;             for (int e = lane; e < 8 * 465; e += 64) rb = fmaxf(rb, fabsf(args.in[11][e]));
; #pragma unroll
;             for (int o = 1; o < 64; o <<= 1) rb = fmaxf(rb, __shfl_xor(rb, o));
;             fastA = __builtin_amdgcn_readfirstlane((64.0f * ga * gk * QSCALE_AB * 1.03f <= 60.0f && sk * LOG2E <= 60.0f) ? 1 : 0) != 0;
;             fastB = __builtin_amdgcn_readfirstlane((64.0f * gb * gl * QSCALE_AB * 1.03f + rb * LOG2E <= 60.0f) ? 1 : 0) != 0;
.LBB0_362:
	s_or_b64 exec, exec, s[0:1]
	s_mov_b64 s[0:1], 0
	s_waitcnt lgkmcnt(0)
	v_mov_b32_e32 v0, 0
	v_mov_b32_e32 v12, 0
	v_mov_b32_e32 v15, 0
	v_mov_b32_e32 v14, 0
	v_mov_b32_e32 v13, 0
	s_barrier
	v_lshrrev_b32_e32 v1, 8, v206
	s_nop 1
	v_readfirstlane_b32 s98, v1
	s_nop 3
	s_cmp_eq_u32 s98, 0
	s_cbranch_scc0 .Lp2_noprio
	s_setprio 1
.Lp2_noprio:
.LBB0_363:
	s_add_u32 s2, s20, s0
	s_addc_u32 s3, s21, s1
	global_load_dwordx4 v[2:5], v0, s[2:3] offset:16
	global_load_dwordx4 v[6:9], v0, s[2:3]
	s_add_u32 s2, s22, s0
	s_addc_u32 s3, s23, s1
	global_load_dwordx4 v[16:19], v0, s[2:3]
	global_load_dwordx4 v[20:23], v0, s[2:3] offset:16
	s_add_u32 s2, s38, s0
	s_addc_u32 s3, s39, s1
	global_load_dwordx4 v[24:27], v0, s[2:3]
	global_load_dwordx4 v[28:31], v0, s[2:3] offset:16
	s_add_u32 s2, s40, s0
	s_addc_u32 s3, s41, s1
	global_load_dwordx4 v[32:35], v0, s[2:3]
	global_load_dwordx4 v[36:39], v0, s[2:3] offset:16
	s_add_u32 s0, s0, 32
	s_addc_u32 s1, s1, 0
	s_cmpk_eq_i32 s0, 0x100
	s_waitcnt vmcnt(6)
	v_max3_f32 v1, v14, |v6|, |v7|
	v_max3_f32 v1, v1, |v8|, |v9|
	s_waitcnt vmcnt(5)
	v_max3_f32 v6, v15, |v16|, |v17|
	v_max3_f32 v1, v1, |v2|, |v3|
	v_max3_f32 v2, v6, |v18|, |v19|
	v_max3_f32 v14, v1, |v4|, |v5|
	s_waitcnt vmcnt(3)
	v_max3_f32 v1, v12, |v24|, |v25|
	v_max3_f32 v2, v2, |v20|, |v21|
	v_max3_f32 v1, v1, |v26|, |v27|
	v_max3_f32 v15, v2, |v22|, |v23|
	s_waitcnt vmcnt(1)
	v_max3_f32 v2, v13, |v32|, |v33|
	v_max3_f32 v1, v1, |v28|, |v29|
	v_max3_f32 v2, v2, |v34|, |v35|
	v_max3_f32 v12, v1, |v30|, |v31|
	s_waitcnt vmcnt(0)
	v_max3_f32 v1, v2, |v36|, |v37|
	v_max3_f32 v13, v1, |v38|, |v39|
	s_cbranch_scc0 .LBB0_363
	v_mov_b32_e32 v9, 0
	global_load_dwordx4 v[0:3], v9, s[36:37] offset:16
	global_load_dwordx4 v[4:7], v9, s[36:37]
	v_sub_u32_e32 v8, 0xe87, v128
	v_lshrrev_b32_e32 v8, 6, v8
	v_add_u32_e32 v17, 1, v8
	v_or_b32_e32 v129, 64, v128
	v_and_b32_e32 v16, 62, v17
	s_mov_b32 s6, 2
	s_mov_b64 s[4:5], 0
	v_mov_b64_e32 v[10:11], v[128:129]
	v_mov_b32_e32 v20, 0
	v_mov_b32_e32 v21, 0
	v_lshlrev_b32_e32 v8, 2, v128
	v_mov_b32_e32 v10, 0
	global_load_dword v16, v8, s[42:43]
	global_load_dword v17, v8, s[42:43] offset:256
	global_load_dword v18, v8, s[42:43] offset:512
	global_load_dword v19, v8, s[42:43] offset:768
	global_load_dword v20, v8, s[42:43] offset:1024
	global_load_dword v21, v8, s[42:43] offset:1280
	global_load_dword v22, v8, s[42:43] offset:1536
	global_load_dword v23, v8, s[42:43] offset:1792
	global_load_dword v24, v8, s[42:43] offset:2048
	global_load_dword v25, v8, s[42:43] offset:2304
	global_load_dword v26, v8, s[42:43] offset:2560
	global_load_dword v27, v8, s[42:43] offset:2816
	global_load_dword v28, v8, s[42:43] offset:3072
	global_load_dword v29, v8, s[42:43] offset:3328
	global_load_dword v30, v8, s[42:43] offset:3584
	global_load_dword v31, v8, s[42:43] offset:3840
	s_waitcnt vmcnt(0)
	v_max3_f32 v10, v10, |v16|, |v17|
	v_max3_f32 v10, v10, |v18|, |v19|
	v_max3_f32 v10, v10, |v20|, |v21|
	v_max3_f32 v10, v10, |v22|, |v23|
	v_max3_f32 v10, v10, |v24|, |v25|
	v_max3_f32 v10, v10, |v26|, |v27|
	v_max3_f32 v10, v10, |v28|, |v29|
	v_max3_f32 v10, v10, |v30|, |v31|
	v_add_u32_e32 v8, 0x1000, v8
	global_load_dword v16, v8, s[42:43]
	global_load_dword v17, v8, s[42:43] offset:256
	global_load_dword v18, v8, s[42:43] offset:512
	global_load_dword v19, v8, s[42:43] offset:768
	global_load_dword v20, v8, s[42:43] offset:1024
	global_load_dword v21, v8, s[42:43] offset:1280
	global_load_dword v22, v8, s[42:43] offset:1536
	global_load_dword v23, v8, s[42:43] offset:1792
	global_load_dword v24, v8, s[42:43] offset:2048
	global_load_dword v25, v8, s[42:43] offset:2304
	global_load_dword v26, v8, s[42:43] offset:2560
	global_load_dword v27, v8, s[42:43] offset:2816
	global_load_dword v28, v8, s[42:43] offset:3072
	global_load_dword v29, v8, s[42:43] offset:3328
	global_load_dword v30, v8, s[42:43] offset:3584
	global_load_dword v31, v8, s[42:43] offset:3840
	s_waitcnt vmcnt(0)
	v_max3_f32 v10, v10, |v16|, |v17|
	v_max3_f32 v10, v10, |v18|, |v19|
	v_max3_f32 v10, v10, |v20|, |v21|
	v_max3_f32 v10, v10, |v22|, |v23|
	v_max3_f32 v10, v10, |v24|, |v25|
	v_max3_f32 v10, v10, |v26|, |v27|
	v_max3_f32 v10, v10, |v28|, |v29|
	v_max3_f32 v10, v10, |v30|, |v31|
	v_add_u32_e32 v8, 0x1000, v8
	global_load_dword v16, v8, s[42:43]
	global_load_dword v17, v8, s[42:43] offset:256
	global_load_dword v18, v8, s[42:43] offset:512
	global_load_dword v19, v8, s[42:43] offset:768
	global_load_dword v20, v8, s[42:43] offset:1024
	global_load_dword v21, v8, s[42:43] offset:1280
	global_load_dword v22, v8, s[42:43] offset:1536
	global_load_dword v23, v8, s[42:43] offset:1792
	global_load_dword v24, v8, s[42:43] offset:2048
	global_load_dword v25, v8, s[42:43] offset:2304
	global_load_dword v26, v8, s[42:43] offset:2560
	global_load_dword v27, v8, s[42:43] offset:2816
	global_load_dword v28, v8, s[42:43] offset:3072
	global_load_dword v29, v8, s[42:43] offset:3328
	global_load_dword v30, v8, s[42:43] offset:3584
	global_load_dword v31, v8, s[42:43] offset:3840
	s_waitcnt vmcnt(0)
	v_max3_f32 v10, v10, |v16|, |v17|
	v_max3_f32 v10, v10, |v18|, |v19|
	v_max3_f32 v10, v10, |v20|, |v21|
	v_max3_f32 v10, v10, |v22|, |v23|
	v_max3_f32 v10, v10, |v24|, |v25|
	v_max3_f32 v10, v10, |v26|, |v27|
	v_max3_f32 v10, v10, |v28|, |v29|
	v_max3_f32 v10, v10, |v30|, |v31|
	v_add_u32_e32 v8, 0x1000, v8
	global_load_dword v16, v8, s[42:43]
	global_load_dword v17, v8, s[42:43] offset:256
	global_load_dword v18, v8, s[42:43] offset:512
	global_load_dword v19, v8, s[42:43] offset:768
	global_load_dword v20, v8, s[42:43] offset:1024
	global_load_dword v21, v8, s[42:43] offset:1280
	global_load_dword v22, v8, s[42:43] offset:1536
	global_load_dword v23, v8, s[42:43] offset:1792
	global_load_dword v24, v8, s[42:43] offset:2048
	global_load_dword v25, v8, s[42:43] offset:2304
	v_mov_b32_e32 v26, 0
	v_cmp_gt_u32_e32 vcc, 8, v128
	s_and_saveexec_b64 s[4:5], vcc
	global_load_dword v26, v8, s[42:43] offset:2560
	s_or_b64 exec, exec, s[4:5]
	s_waitcnt vmcnt(0)
	v_max3_f32 v10, v10, |v16|, |v17|
	v_max3_f32 v10, v10, |v18|, |v19|
	v_max3_f32 v10, v10, |v20|, |v21|
	v_max3_f32 v10, v10, |v22|, |v23|
	v_max3_f32 v10, v10, |v24|, |v25|
	v_max_f32_e64 v11, |v26|, |v26|
	v_max_f32_e32 v10, v10, v11

; __device__ __forceinline__ void xcd_barrier(const XcdBarrier& b) {
;     asm volatile("s_waitcnt vmcnt(0)" ::: "memory");
;     __syncthreads();
;     if (threadIdx.x == 0) {
;         unsigned* bar = b.bar;
;         __builtin_amdgcn_s_waitcnt(0);
;         unsigned nloc = b.st[0], nx = b.st[1];
;         if (nloc == 0u) { xcd_barrier_complete(bar, b.x, nloc, nx); b.st[0] = nloc; b.st[1] = nx; }
.LBB0_470:
	s_setprio 0
	s_waitcnt vmcnt(0)
	s_waitcnt lgkmcnt(0)
	s_barrier
	s_mov_b64 s[0:1], exec
	v_readlane_b32 s2, v247, 2
	v_readlane_b32 s3, v247, 3
	s_and_b64 s[2:3], s[0:1], s[2:3]
	s_mov_b64 exec, s[2:3]
	s_cbranch_execz .LBB0_522
	s_add_i32 s2, 0, 0x23fe0
	v_mov_b32_e32 v0, s2
	s_waitcnt vmcnt(0) expcnt(0) lgkmcnt(0)
	ds_read_b32 v2, v0
	s_add_i32 s2, 0, 0x23fe4
	v_mov_b32_e32 v0, s2
	ds_read_b32 v0, v0
	s_waitcnt lgkmcnt(1)
	v_cmp_ne_u32_e32 vcc, 0, v2
	s_cbranch_vccnz .LBB0_486
	v_readlane_b32 s2, v247, 0
	s_mul_i32 s16, s89, s2
	s_add_u32 s2, s90, 0x1000
	s_addc_u32 s3, s91, 0
	s_add_u32 s4, s90, 0x1100
	s_addc_u32 s5, s91, 0
	s_add_u32 s6, s90, 0x1200
	s_addc_u32 s7, s91, 0
	s_add_u32 s8, s90, 0x1300
	s_mul_i32 s16, s16, s88
	s_addc_u32 s9, s91, 0
	s_mov_b32 s17, 1
	v_mov_b32_e32 v16, 0
	s_branch .LBB0_474
